# branch GEMM: first-row-half gate lines touched from the unit's last K iteration (one dword load per wave behind phase 2's DMA loads)
# speedup vs baseline: 1.0010x; 1.0010x over previous
; #define PG8_STAGE(bufoff, gbase, voff) do { _Pragma("unroll") for (int _i = 0; _i < 2; ++_i) \
;         __builtin_amdgcn_global_load_lds((const unsigned*)((const char*)(gbase) + (voff)[_i]), (LAS unsigned*)(lds + (bufoff) + ldsw + _i * 8192), 16, 0, 0); } while (0)
; #define PG8_LDA(dst, b, h) do { _Pragma("unroll") for (int m = 0; m < 4; ++m) _Pragma("unroll") for (int k = 0; k < 2; ++k) dst[m][k] = *(const LAS bf16x8*)(lds + PG8_SA(b, h) + aoff + m * 2048 + k * 1024); } while (0)
; #define PG8_LDB(dst, b, h) do { _Pragma("unroll") for (int n = 0; n < 2; ++n) _Pragma("unroll") for (int k = 0; k < 2; ++k) dst[n][k] = *(const LAS bf16x8*)(lds + PG8_SB(b, h) + boff + n * 2048 + k * 1024); } while (0)
; #define PG8_MMA(ai, bj, At, Bt) do { __builtin_amdgcn_s_setprio(1); _Pragma("unroll") for (int m = 0; m < 4; ++m) _Pragma("unroll") for (int n = 0; n < 2; ++n) _Pragma("unroll") for (int k = 0; k < 2; ++k) \
;         acc[ai][bj][m][n] = __builtin_amdgcn_mfma_f32_16x16x32_bf16(Bt[n][k], At[m][k], acc[ai][bj][m][n], 0, 0, 0); __builtin_amdgcn_s_setprio(0); } while (0)
; #define PG8_WAIT_V(n) asm volatile("s_waitcnt vmcnt(" #n ")" ::: "memory")
; #define PG8_WAIT_L(n) asm volatile("s_waitcnt lgkmcnt(" #n ")" ::: "memory")
; template <class Epi, class Sched>
; __device__ __forceinline__ void gemm_phase(LAS unsigned char* lds, const Gemm g, const Sched& S, const Epi& E) {
;     ...
;         for (int t = 0; t < nt; t += 2) {
;             const bool last = (t == nt - 2);
;             const char* a1 = cA + (size_t)(t + 1) * kstep;
;             const char* a2 = last ? nA : cA + (size_t)(t + 2) * kstep; const char* b2 = last ? nB : cB + (size_t)(t + 2) * kstep;
;             const char* a3 = a2 + kstep; const char* b3 = b2 + kstep;
;             PG8_LDB(B0, 0, 0); PG8_SCHED; PG8_LDA(At, 0, 0); PG8_STAGE(PG8_SA(1, 1), a1 + hstep, voffA);
;             PG8_WAIT_L(8); PG8_BAR; PG8_WAIT_L(0); PG8_MMA(0, 0, At, B0); PG8_BAR; PG8_SCHED;
;             PG8_LDB(B1, 0, 1); PG8_STAGE(PG8_SB(0, 0), b2, voffB);
;             PG8_BAR; PG8_WAIT_L(0); PG8_MMA(0, 1, At, B1); PG8_BAR;
;             PG8_LDA(At, 0, 1); PG8_STAGE(PG8_SA(0, 0), a2, voffA);
;             PG8_BAR; PG8_WAIT_L(0); PG8_MMA(1, 0, At, B0); PG8_BAR; PG8_SCHED;
;             PG8_STAGE(PG8_SB(0, 1), b2 + hstep, voffB);
;             PG8_WAIT_V(6); PG8_BAR; PG8_MMA(1, 1, At, B1); PG8_BAR;
.LBB0_23:
	s_add_u32 s22, s20, 0xfffe0080
	s_addc_u32 s23, s21, -1
	s_add_i32 s43, 0, 0x10000
	v_add_u32_e32 v156, s43, v211
	ds_read_b128 v[144:147], v156
	ds_read_b128 v[148:151], v156 offset:1024
	ds_read_b128 v[152:155], v156 offset:2048
	ds_read_b128 v[156:159], v156 offset:3072
	s_cmp_eq_u32 s42, 4
	s_cselect_b32 s25, s1, s23
	s_cselect_b32 s24, s37, s22
	s_cselect_b32 s23, s38, s41
	s_cselect_b32 s22, s39, s40
	v_lshl_add_u64 v[160:161], s[20:21], 0, v[140:141]
	s_add_i32 m0, s28, 0xc000
	ds_read_b128 v[172:175], v212
	ds_read_b128 v[176:179], v212 offset:1024
	ds_read_b128 v[180:183], v212 offset:2048
	ds_read_b128 v[184:187], v212 offset:3072
	ds_read_b128 v[188:191], v212 offset:4096
	ds_read_b128 v[192:195], v212 offset:5120
	ds_read_b128 v[214:217], v212 offset:6144
	ds_read_b128 v[218:221], v212 offset:7168
	global_load_lds_dwordx4 v[160:161], off
	v_lshl_add_u64 v[160:161], s[20:21], 0, v[142:143]
	s_add_i32 m0, s28, 0xe000
	s_nop 0
	global_load_lds_dwordx4 v[160:161], off
	s_waitcnt lgkmcnt(8)
	s_barrier
	s_waitcnt lgkmcnt(0)
	s_setprio 1
	s_waitcnt lgkmcnt(0)
	v_mfma_f32_16x16x32_bf16 v[126:129], v[144:147], v[172:175], v[126:129]
	v_mfma_f32_16x16x32_bf16 v[122:125], v[152:155], v[172:175], v[122:125]
	v_mfma_f32_16x16x32_bf16 v[118:121], v[144:147], v[180:183], v[118:121]
	v_mfma_f32_16x16x32_bf16 v[114:117], v[152:155], v[180:183], v[114:117]
	v_mfma_f32_16x16x32_bf16 v[110:113], v[144:147], v[188:191], v[110:113]
	v_mfma_f32_16x16x32_bf16 v[106:109], v[152:155], v[188:191], v[106:109]
	v_mfma_f32_16x16x32_bf16 v[102:105], v[144:147], v[214:217], v[102:105]
	v_mfma_f32_16x16x32_bf16 v[98:101], v[152:155], v[214:217], v[98:101]
	v_mfma_f32_16x16x32_bf16 v[126:129], v[148:151], v[176:179], v[126:129]
	v_mfma_f32_16x16x32_bf16 v[122:125], v[156:159], v[176:179], v[122:125]
	v_mfma_f32_16x16x32_bf16 v[118:121], v[148:151], v[184:187], v[118:121]
	v_mfma_f32_16x16x32_bf16 v[114:117], v[156:159], v[184:187], v[114:117]
	v_mfma_f32_16x16x32_bf16 v[110:113], v[148:151], v[192:195], v[110:113]
	v_mfma_f32_16x16x32_bf16 v[106:109], v[156:159], v[192:195], v[106:109]
	v_mfma_f32_16x16x32_bf16 v[102:105], v[148:151], v[218:221], v[102:105]
	v_mfma_f32_16x16x32_bf16 v[98:101], v[156:159], v[218:221], v[98:101]
	s_setprio 0
	s_barrier
	s_add_i32 s55, 0, 0x14000
	v_add_u32_e32 v160, s55, v211
	s_add_i32 s43, s43, s27
	ds_read_b128 v[222:225], v160
	ds_read_b128 v[226:229], v160 offset:1024
	ds_read_b128 v[230:233], v160 offset:2048
	ds_read_b128 v[234:237], v160 offset:3072
	v_lshl_add_u64 v[160:161], s[22:23], 0, v[134:135]
	s_mov_b32 m0, s43
	v_lshl_add_u64 v[196:197], s[22:23], 0, v[130:131]
	global_load_lds_dwordx4 v[160:161], off
	s_add_i32 m0, s43, 0x2000
	s_nop 0
	global_load_lds_dwordx4 v[196:197], off
	s_cmp_eq_u32 s42, 4
	s_cbranch_scc0 .Lg3pf_skip
	v_bfe_u32 v244, v198, 2, 7
	v_lshl_add_u32 v244, s30, 8, v244
	v_lshlrev_b32_e32 v244, 12, v244
	v_and_b32_e32 v245, 1, v198
	v_lshl_add_u32 v244, v245, 7, v244
	s_cmp_gt_u32 s54, 11
	s_cbranch_scc1 .Lg3pf_last
	v_and_b32_e32 v245, 2, v198
	v_lshl_add_u32 v244, v245, 9, v244
.Lg3pf_last:
	v_mov_b32_e32 v245, s54
	v_lshl_add_u32 v244, v245, 8, v244
	v_mov_b32_e32 v245, 0
	v_lshl_add_u64 v[242:243], v[138:139], 0, v[244:245]
	global_load_dword v248, v[242:243], off
.Lg3pf_skip:
	s_barrier
	s_waitcnt lgkmcnt(0)
	s_setprio 1
	s_waitcnt lgkmcnt(0)
	v_mfma_f32_16x16x32_bf16 v[94:97], v[222:225], v[172:175], v[94:97]
	v_mfma_f32_16x16x32_bf16 v[90:93], v[230:233], v[172:175], v[90:93]
	v_mfma_f32_16x16x32_bf16 v[86:89], v[222:225], v[180:183], v[86:89]
	v_mfma_f32_16x16x32_bf16 v[82:85], v[230:233], v[180:183], v[82:85]
	v_mfma_f32_16x16x32_bf16 v[78:81], v[222:225], v[188:191], v[78:81]
	v_mfma_f32_16x16x32_bf16 v[74:77], v[230:233], v[188:191], v[74:77]
	v_mfma_f32_16x16x32_bf16 v[70:73], v[222:225], v[214:217], v[70:73]
	v_mfma_f32_16x16x32_bf16 v[66:69], v[230:233], v[214:217], v[66:69]
	v_mfma_f32_16x16x32_bf16 v[94:97], v[226:229], v[176:179], v[94:97]
	v_mfma_f32_16x16x32_bf16 v[90:93], v[234:237], v[176:179], v[90:93]
	v_mfma_f32_16x16x32_bf16 v[86:89], v[226:229], v[184:187], v[86:89]
	v_mfma_f32_16x16x32_bf16 v[82:85], v[234:237], v[184:187], v[82:85]
	v_mfma_f32_16x16x32_bf16 v[78:81], v[226:229], v[192:195], v[78:81]
	v_mfma_f32_16x16x32_bf16 v[74:77], v[234:237], v[192:195], v[74:77]
	v_mfma_f32_16x16x32_bf16 v[70:73], v[226:229], v[218:221], v[70:73]
	v_mfma_f32_16x16x32_bf16 v[66:69], v[234:237], v[218:221], v[66:69]
	s_setprio 0
	s_mov_b32 m0, s28
	v_lshl_add_u64 v[238:239], s[24:25], 0, v[136:137]
	s_barrier
	ds_read_b128 v[172:175], v212 offset:16384
	ds_read_b128 v[176:179], v212 offset:17408
	ds_read_b128 v[180:183], v212 offset:18432
	ds_read_b128 v[184:187], v212 offset:19456
	ds_read_b128 v[188:191], v212 offset:20480
	ds_read_b128 v[192:195], v212 offset:21504
	ds_read_b128 v[214:217], v212 offset:22528
	ds_read_b128 v[218:221], v212 offset:23552
	global_load_lds_dwordx4 v[238:239], off
	v_lshl_add_u64 v[240:241], s[24:25], 0, v[132:133]
	s_mov_b32 m0, s29
	s_nop 0
	global_load_lds_dwordx4 v[240:241], off
	s_barrier
	s_waitcnt lgkmcnt(0)
	s_setprio 1
	s_waitcnt lgkmcnt(0)
	v_mfma_f32_16x16x32_bf16 v[62:65], v[144:147], v[172:175], v[62:65]
	v_mfma_f32_16x16x32_bf16 v[58:61], v[152:155], v[172:175], v[58:61]
	v_mfma_f32_16x16x32_bf16 v[54:57], v[144:147], v[180:183], v[54:57]
	v_mfma_f32_16x16x32_bf16 v[50:53], v[152:155], v[180:183], v[50:53]
	v_mfma_f32_16x16x32_bf16 v[46:49], v[144:147], v[188:191], v[46:49]
	v_mfma_f32_16x16x32_bf16 v[42:45], v[152:155], v[188:191], v[42:45]
	v_mfma_f32_16x16x32_bf16 v[38:41], v[144:147], v[214:217], v[38:41]
	v_mfma_f32_16x16x32_bf16 v[34:37], v[152:155], v[214:217], v[34:37]
	v_mfma_f32_16x16x32_bf16 v[62:65], v[148:151], v[176:179], v[62:65]
	v_mfma_f32_16x16x32_bf16 v[58:61], v[156:159], v[176:179], v[58:61]
	v_mfma_f32_16x16x32_bf16 v[54:57], v[148:151], v[184:187], v[54:57]
	v_mfma_f32_16x16x32_bf16 v[50:53], v[156:159], v[184:187], v[50:53]
	v_mfma_f32_16x16x32_bf16 v[46:49], v[148:151], v[192:195], v[46:49]
	v_mfma_f32_16x16x32_bf16 v[42:45], v[156:159], v[192:195], v[42:45]
	v_mfma_f32_16x16x32_bf16 v[38:41], v[148:151], v[218:221], v[38:41]
	v_mfma_f32_16x16x32_bf16 v[34:37], v[156:159], v[218:221], v[34:37]
	s_setprio 0
	s_barrier
	s_add_u32 s56, s22, 0x20000
	s_addc_u32 s57, s23, 0
	s_add_i32 s43, s55, s27
	v_lshl_add_u64 v[144:145], s[56:57], 0, v[134:135]
	s_mov_b32 m0, s43
	s_nop 0
	global_load_lds_dwordx4 v[144:145], off
	v_lshl_add_u64 v[144:145], s[56:57], 0, v[130:131]
	s_add_i32 m0, s43, 0x2000
	s_nop 0
	global_load_lds_dwordx4 v[144:145], off
	s_cmp_eq_u32 s42, 4
	s_cbranch_scc1 .Lg3pf_w7
	s_waitcnt vmcnt(6)
	s_branch .Lg3pf_wd
; #define PG8_STAGE(bufoff, gbase, voff) do { _Pragma("unroll") for (int _i = 0; _i < 2; ++_i) \
;         __builtin_amdgcn_global_load_lds((const unsigned*)((const char*)(gbase) + (voff)[_i]), (LAS unsigned*)(lds + (bufoff) + ldsw + _i * 8192), 16, 0, 0); } while (0)
; #define PG8_LDA(dst, b, h) do { _Pragma("unroll") for (int m = 0; m < 4; ++m) _Pragma("unroll") for (int k = 0; k < 2; ++k) dst[m][k] = *(const LAS bf16x8*)(lds + PG8_SA(b, h) + aoff + m * 2048 + k * 1024); } while (0)
; #define PG8_LDB(dst, b, h) do { _Pragma("unroll") for (int n = 0; n < 2; ++n) _Pragma("unroll") for (int k = 0; k < 2; ++k) dst[n][k] = *(const LAS bf16x8*)(lds + PG8_SB(b, h) + boff + n * 2048 + k * 1024); } while (0)
; #define PG8_MMA(ai, bj, At, Bt) do { __builtin_amdgcn_s_setprio(1); _Pragma("unroll") for (int m = 0; m < 4; ++m) _Pragma("unroll") for (int n = 0; n < 2; ++n) _Pragma("unroll") for (int k = 0; k < 2; ++k) \
;         acc[ai][bj][m][n] = __builtin_amdgcn_mfma_f32_16x16x32_bf16(Bt[n][k], At[m][k], acc[ai][bj][m][n], 0, 0, 0); __builtin_amdgcn_s_setprio(0); } while (0)
; #define PG8_WAIT_V(n) asm volatile("s_waitcnt vmcnt(" #n ")" ::: "memory")
; #define PG8_WAIT_L(n) asm volatile("s_waitcnt lgkmcnt(" #n ")" ::: "memory")
; #define PG8_BAR __builtin_amdgcn_s_barrier()
; #define PG8_SCHED __builtin_amdgcn_sched_barrier(0)
; template <class Epi, class Sched>
; __device__ __forceinline__ void gemm_phase(LAS unsigned char* lds, const Gemm g, const Sched& S, const Epi& E) {
;     ...
;             PG8_WAIT_V(6); PG8_BAR; PG8_MMA(1, 1, At, B1); PG8_BAR;
;             PG8_LDB(B0, 1, 0); PG8_SCHED; PG8_LDA(At, 1, 0); PG8_STAGE(PG8_SA(0, 1), a2 + hstep, voffA);
;             PG8_WAIT_L(8); PG8_BAR; PG8_WAIT_L(0); PG8_MMA(0, 0, At, B0); PG8_BAR; PG8_SCHED;
;             PG8_LDB(B1, 1, 1); PG8_STAGE(PG8_SB(1, 0), b3, voffB);
;             PG8_BAR; PG8_WAIT_L(0); PG8_MMA(0, 1, At, B1); PG8_BAR;
.Lg3pf_w7:
	s_waitcnt vmcnt(7)
.Lg3pf_wd:
	s_barrier
	s_setprio 1
	v_mfma_f32_16x16x32_bf16 v[30:33], v[222:225], v[172:175], v[30:33]
	v_mfma_f32_16x16x32_bf16 v[26:29], v[230:233], v[172:175], v[26:29]
	v_mfma_f32_16x16x32_bf16 v[22:25], v[222:225], v[180:183], v[22:25]
	v_mfma_f32_16x16x32_bf16 v[18:21], v[230:233], v[180:183], v[18:21]
	v_mfma_f32_16x16x32_bf16 v[14:17], v[222:225], v[188:191], v[14:17]
	v_mfma_f32_16x16x32_bf16 v[10:13], v[230:233], v[188:191], v[10:13]
	v_mfma_f32_16x16x32_bf16 v[6:9], v[222:225], v[214:217], v[6:9]
	v_mfma_f32_16x16x32_bf16 v[2:5], v[230:233], v[214:217], v[2:5]
	v_mfma_f32_16x16x32_bf16 v[30:33], v[226:229], v[176:179], v[30:33]
	v_mfma_f32_16x16x32_bf16 v[26:29], v[234:237], v[176:179], v[26:29]
	v_mfma_f32_16x16x32_bf16 v[22:25], v[226:229], v[184:187], v[22:25]
	v_mfma_f32_16x16x32_bf16 v[18:21], v[234:237], v[184:187], v[18:21]
	v_mfma_f32_16x16x32_bf16 v[14:17], v[226:229], v[192:195], v[14:17]
	v_mfma_f32_16x16x32_bf16 v[10:13], v[234:237], v[192:195], v[10:13]
	v_mfma_f32_16x16x32_bf16 v[6:9], v[226:229], v[218:221], v[6:9]
	v_mfma_f32_16x16x32_bf16 v[2:5], v[234:237], v[218:221], v[2:5]
	s_setprio 0
	s_add_i32 s43, 0, 0x18000
	v_add_u32_e32 v156, s43, v211
	s_barrier
	ds_read_b128 v[144:147], v156
	ds_read_b128 v[148:151], v156 offset:1024
	ds_read_b128 v[152:155], v156 offset:2048
	ds_read_b128 v[156:159], v156 offset:3072
	s_add_u32 s24, s24, 0x20000
	s_addc_u32 s25, s25, 0
	s_mov_b32 m0, s44
	v_lshl_add_u64 v[222:223], s[24:25], 0, v[136:137]
	ds_read_b128 v[172:175], v212 offset:32768
	ds_read_b128 v[176:179], v212 offset:33792
	ds_read_b128 v[180:183], v212 offset:34816
	ds_read_b128 v[184:187], v212 offset:35840
	ds_read_b128 v[188:191], v212 offset:36864
	ds_read_b128 v[192:195], v212 offset:37888
	ds_read_b128 v[214:217], v212 offset:38912
	ds_read_b128 v[218:221], v212 offset:39936
	global_load_lds_dwordx4 v[222:223], off
	v_lshl_add_u64 v[222:223], s[24:25], 0, v[132:133]
	s_mov_b32 m0, s45
	s_nop 0
	global_load_lds_dwordx4 v[222:223], off
	s_waitcnt lgkmcnt(8)
	s_barrier
	s_waitcnt lgkmcnt(0)
	s_setprio 1
	s_waitcnt lgkmcnt(0)
	v_mfma_f32_16x16x32_bf16 v[126:129], v[144:147], v[172:175], v[126:129]
	v_mfma_f32_16x16x32_bf16 v[122:125], v[152:155], v[172:175], v[122:125]
	v_mfma_f32_16x16x32_bf16 v[118:121], v[144:147], v[180:183], v[118:121]
	v_mfma_f32_16x16x32_bf16 v[114:117], v[152:155], v[180:183], v[114:117]
	v_mfma_f32_16x16x32_bf16 v[110:113], v[144:147], v[188:191], v[110:113]
	v_mfma_f32_16x16x32_bf16 v[106:109], v[152:155], v[188:191], v[106:109]
	v_mfma_f32_16x16x32_bf16 v[102:105], v[144:147], v[214:217], v[102:105]
	v_mfma_f32_16x16x32_bf16 v[98:101], v[152:155], v[214:217], v[98:101]
	v_mfma_f32_16x16x32_bf16 v[126:129], v[148:151], v[176:179], v[126:129]
	v_mfma_f32_16x16x32_bf16 v[122:125], v[156:159], v[176:179], v[122:125]
	v_mfma_f32_16x16x32_bf16 v[118:121], v[148:151], v[184:187], v[118:121]
	v_mfma_f32_16x16x32_bf16 v[114:117], v[156:159], v[184:187], v[114:117]
	v_mfma_f32_16x16x32_bf16 v[110:113], v[148:151], v[192:195], v[110:113]
	v_mfma_f32_16x16x32_bf16 v[106:109], v[156:159], v[192:195], v[106:109]
	v_mfma_f32_16x16x32_bf16 v[102:105], v[148:151], v[218:221], v[102:105]
	v_mfma_f32_16x16x32_bf16 v[98:101], v[156:159], v[218:221], v[98:101]
	s_setprio 0
	s_barrier
	s_add_i32 s24, 0, 0x1c000
	s_add_i32 s25, s43, s27
	v_add_u32_e32 v213, s24, v211
	v_lshl_add_u64 v[160:161], v[160:161], 0, s[2:3]
	s_mov_b32 m0, s25
	ds_read_b128 v[222:225], v213
	ds_read_b128 v[226:229], v213 offset:1024
	ds_read_b128 v[230:233], v213 offset:2048
	ds_read_b128 v[234:237], v213 offset:3072
	global_load_lds_dwordx4 v[160:161], off
	v_lshl_add_u64 v[160:161], v[196:197], 0, s[2:3]
	s_add_i32 m0, s25, 0x2000
	s_nop 0
	global_load_lds_dwordx4 v[160:161], off
	s_barrier
	s_waitcnt lgkmcnt(0)
	s_setprio 1
	s_waitcnt lgkmcnt(0)
	v_mfma_f32_16x16x32_bf16 v[94:97], v[222:225], v[172:175], v[94:97]
	v_mfma_f32_16x16x32_bf16 v[90:93], v[230:233], v[172:175], v[90:93]
	v_mfma_f32_16x16x32_bf16 v[86:89], v[222:225], v[180:183], v[86:89]
	v_mfma_f32_16x16x32_bf16 v[82:85], v[230:233], v[180:183], v[82:85]
	v_mfma_f32_16x16x32_bf16 v[78:81], v[222:225], v[188:191], v[78:81]
	v_mfma_f32_16x16x32_bf16 v[74:77], v[230:233], v[188:191], v[74:77]
	v_mfma_f32_16x16x32_bf16 v[70:73], v[222:225], v[214:217], v[70:73]
	v_mfma_f32_16x16x32_bf16 v[66:69], v[230:233], v[214:217], v[66:69]
	v_mfma_f32_16x16x32_bf16 v[94:97], v[226:229], v[176:179], v[94:97]
	v_mfma_f32_16x16x32_bf16 v[90:93], v[234:237], v[176:179], v[90:93]
	v_mfma_f32_16x16x32_bf16 v[86:89], v[226:229], v[184:187], v[86:89]
	v_mfma_f32_16x16x32_bf16 v[82:85], v[234:237], v[184:187], v[82:85]
	v_mfma_f32_16x16x32_bf16 v[78:81], v[226:229], v[192:195], v[78:81]
	v_mfma_f32_16x16x32_bf16 v[74:77], v[234:237], v[192:195], v[74:77]
	v_mfma_f32_16x16x32_bf16 v[70:73], v[226:229], v[218:221], v[70:73]
	v_mfma_f32_16x16x32_bf16 v[66:69], v[234:237], v[218:221], v[66:69]
	s_setprio 0
	s_mov_b32 m0, s50
	v_lshl_add_u64 v[160:161], v[238:239], 0, s[2:3]
	s_barrier
; #define PG8_STAGE(bufoff, gbase, voff) do { _Pragma("unroll") for (int _i = 0; _i < 2; ++_i) \
;         __builtin_amdgcn_global_load_lds((const unsigned*)((const char*)(gbase) + (voff)[_i]), (LAS unsigned*)(lds + (bufoff) + ldsw + _i * 8192), 16, 0, 0); } while (0)
; #define PG8_LDA(dst, b, h) do { _Pragma("unroll") for (int m = 0; m < 4; ++m) _Pragma("unroll") for (int k = 0; k < 2; ++k) dst[m][k] = *(const LAS bf16x8*)(lds + PG8_SA(b, h) + aoff + m * 2048 + k * 1024); } while (0)
; #define PG8_MMA(ai, bj, At, Bt) do { __builtin_amdgcn_s_setprio(1); _Pragma("unroll") for (int m = 0; m < 4; ++m) _Pragma("unroll") for (int n = 0; n < 2; ++n) _Pragma("unroll") for (int k = 0; k < 2; ++k) \
;         acc[ai][bj][m][n] = __builtin_amdgcn_mfma_f32_16x16x32_bf16(Bt[n][k], At[m][k], acc[ai][bj][m][n], 0, 0, 0); __builtin_amdgcn_s_setprio(0); } while (0)
; #define PG8_WAIT_V(n) asm volatile("s_waitcnt vmcnt(" #n ")" ::: "memory")
; #define PG8_WAIT_L(n) asm volatile("s_waitcnt lgkmcnt(" #n ")" ::: "memory")
; #define PG8_BAR __builtin_amdgcn_s_barrier()
; #define PG8_SCHED __builtin_amdgcn_sched_barrier(0)
; template <class Epi, class Sched>
; __device__ __forceinline__ void gemm_phase(LAS unsigned char* lds, const Gemm g, const Sched& S, const Epi& E) {
;     ...
;             PG8_BAR; PG8_WAIT_L(0); PG8_MMA(0, 1, At, B1); PG8_BAR;
;             PG8_LDA(At, 1, 1); PG8_STAGE(PG8_SA(1, 0), a3, voffA);
;             PG8_BAR; PG8_WAIT_L(0); PG8_MMA(1, 0, At, B0); PG8_BAR; PG8_SCHED;
;             PG8_STAGE(PG8_SB(1, 1), b3 + hstep, voffB);
;             PG8_WAIT_V(6); PG8_BAR; PG8_MMA(1, 1, At, B1); PG8_BAR;
;     __device__ __forceinline__ void operator()(f32x4 (&acc)[2][2][4][2], const pg8::Unit& u, int wr, int wc, int fr, int fq) const {
;         const int row0 = u.pm * 256 + wr * 64 + fr, cin = wc * 32 + 8 * fq; const bool last = (u.pn >= 12);
; #pragma unroll
;         for (int ai = 0; ai < 2; ++ai) {
;             u32x2 ga[4][2], gb[4][2];
; #pragma unroll
;             for (int m = 0; m < 4; ++m) {
;                 const unsigned char* gp = gq + (size_t)(row0 + ai * 128 + m * 16) * 4096 + u.pn * 256 + cin;
; #pragma unroll
;                 for (int bj = 0; bj < 2; ++bj) { ga[m][bj] = *(const u32x2*)(gp + bj * 128);
;                     gb[m][bj] = last ? (u32x2){0x01010101u, 0x01010101u} : *(const u32x2*)(gp + 1024 + bj * 128); }
	ds_read_b128 v[172:175], v212 offset:49152
	ds_read_b128 v[176:179], v212 offset:50176
	ds_read_b128 v[180:183], v212 offset:51200
	ds_read_b128 v[184:187], v212 offset:52224
	ds_read_b128 v[188:191], v212 offset:53248
	ds_read_b128 v[192:195], v212 offset:54272
	ds_read_b128 v[214:217], v212 offset:55296
	ds_read_b128 v[218:221], v212 offset:56320
	global_load_lds_dwordx4 v[160:161], off
	v_lshl_add_u64 v[160:161], v[240:241], 0, s[2:3]
	s_mov_b32 m0, s51
	s_nop 0
	global_load_lds_dwordx4 v[160:161], off
	s_barrier
	s_waitcnt lgkmcnt(0)
	s_setprio 1
	s_waitcnt lgkmcnt(0)
	v_mfma_f32_16x16x32_bf16 v[62:65], v[144:147], v[172:175], v[62:65]
	v_mfma_f32_16x16x32_bf16 v[58:61], v[152:155], v[172:175], v[58:61]
	v_mfma_f32_16x16x32_bf16 v[54:57], v[144:147], v[180:183], v[54:57]
	v_mfma_f32_16x16x32_bf16 v[50:53], v[152:155], v[180:183], v[50:53]
	v_mfma_f32_16x16x32_bf16 v[46:49], v[144:147], v[188:191], v[46:49]
	v_mfma_f32_16x16x32_bf16 v[42:45], v[152:155], v[188:191], v[42:45]
	v_mfma_f32_16x16x32_bf16 v[38:41], v[144:147], v[214:217], v[38:41]
	v_mfma_f32_16x16x32_bf16 v[34:37], v[152:155], v[214:217], v[34:37]
	v_mfma_f32_16x16x32_bf16 v[62:65], v[148:151], v[176:179], v[62:65]
	v_mfma_f32_16x16x32_bf16 v[58:61], v[156:159], v[176:179], v[58:61]
	v_mfma_f32_16x16x32_bf16 v[54:57], v[148:151], v[184:187], v[54:57]
	v_mfma_f32_16x16x32_bf16 v[50:53], v[156:159], v[184:187], v[50:53]
	v_mfma_f32_16x16x32_bf16 v[46:49], v[148:151], v[192:195], v[46:49]
	v_mfma_f32_16x16x32_bf16 v[42:45], v[156:159], v[192:195], v[42:45]
	v_mfma_f32_16x16x32_bf16 v[38:41], v[148:151], v[218:221], v[38:41]
	v_mfma_f32_16x16x32_bf16 v[34:37], v[156:159], v[218:221], v[34:37]
	s_setprio 0
	s_barrier
	s_add_u32 s22, s22, 0x20080
	s_addc_u32 s23, s23, 0
	s_add_i32 s24, s24, s27
	v_lshl_add_u64 v[144:145], s[22:23], 0, v[134:135]
	s_mov_b32 m0, s24
	s_nop 0
	global_load_lds_dwordx4 v[144:145], off
	v_lshl_add_u64 v[144:145], s[22:23], 0, v[130:131]
	s_add_i32 m0, s24, 0x2000
	s_nop 0
	global_load_lds_dwordx4 v[144:145], off
	s_waitcnt vmcnt(6)
	s_barrier
	s_setprio 1
	v_mfma_f32_16x16x32_bf16 v[30:33], v[222:225], v[172:175], v[30:33]
	v_mfma_f32_16x16x32_bf16 v[26:29], v[230:233], v[172:175], v[26:29]
	v_mfma_f32_16x16x32_bf16 v[22:25], v[222:225], v[180:183], v[22:25]
	v_mfma_f32_16x16x32_bf16 v[18:21], v[230:233], v[180:183], v[18:21]
	v_mfma_f32_16x16x32_bf16 v[14:17], v[222:225], v[188:191], v[14:17]
	v_mfma_f32_16x16x32_bf16 v[10:13], v[230:233], v[188:191], v[10:13]
	v_mfma_f32_16x16x32_bf16 v[6:9], v[222:225], v[214:217], v[6:9]
	v_mfma_f32_16x16x32_bf16 v[2:5], v[230:233], v[214:217], v[2:5]
	v_mfma_f32_16x16x32_bf16 v[30:33], v[226:229], v[176:179], v[30:33]
	v_mfma_f32_16x16x32_bf16 v[26:29], v[234:237], v[176:179], v[26:29]
	v_mfma_f32_16x16x32_bf16 v[22:25], v[226:229], v[184:187], v[22:25]
	v_mfma_f32_16x16x32_bf16 v[18:21], v[234:237], v[184:187], v[18:21]
	v_mfma_f32_16x16x32_bf16 v[14:17], v[226:229], v[192:195], v[14:17]
	v_mfma_f32_16x16x32_bf16 v[10:13], v[234:237], v[192:195], v[10:13]
	v_mfma_f32_16x16x32_bf16 v[6:9], v[226:229], v[218:221], v[6:9]
	v_mfma_f32_16x16x32_bf16 v[2:5], v[234:237], v[218:221], v[2:5]
	s_setprio 0
	s_add_i32 s42, s42, 2
	s_add_u32 s20, s20, 0x100
	s_addc_u32 s21, s21, 0
	s_add_u32 s40, s40, 0x100
	s_addc_u32 s41, s41, 0
	s_cmp_gt_u32 s42, 5
	s_barrier
	s_cbranch_scc0 .LBB0_23
	s_cmp_gt_u32 s54, 11
	v_lshl_add_u32 v144, s30, 8, v163
	s_cselect_b64 s[38:39], -1, 0
	s_cmp_lt_u32 s54, 12
	s_cselect_b64 s[20:21], -1, 0
	s_lshl_b32 s30, s54, 8
	v_ashrrev_i32_e32 v145, 31, v144
	v_lshl_add_u64 v[146:147], v[138:139], 0, s[30:31]
	v_lshlrev_b64 v[148:149], 12, v[144:145]
	v_lshl_add_u64 v[148:149], v[146:147], 0, v[148:149]
	global_load_dwordx2 v[192:193], v[148:149], off
	v_mov_b32_e32 v188, 0x1010101
	s_and_b64 vcc, exec, s[38:39]
	v_mov_b32_e32 v196, 0x1010101
	v_mov_b32_e32 v197, 0x1010101
	s_cbranch_vccnz .LBB0_26
	global_load_dwordx2 v[196:197], v[148:149], off offset:1024
